# P5 final epilogue hand-written: packed gate multiply + lane-transposed bf16 tile stores
# speedup vs baseline: 1.0068x; 1.0025x over previous
; DI unsigned cvtpk(float lo, float hi) { unsigned r; asm volatile("v_cvt_pk_bf16_f32 %0, %1, %2" : "=v"(r) : "v"(lo), "v"(hi)); return r; }
; DI float ub(unsigned w, int i) { return (float)((w >> (8 * i)) & 0xffu); }
;     DI void operator()(const f32x4 (&acc)[2][2][4][2], const pg8::Unit& u, int wr, int wc, int fr, int fq) const {
;         const unsigned char* zm = ws + WS_ZM; unsigned char* mg = ws + WS_MRG;
;         unsigned r0_ = (unsigned)(u.pm * 256 + wr * 64 + fr), c0_ = (unsigned)(wc * 32 + 8 * fq);
;         asm volatile("" : "+v"(r0_), "+v"(c0_));
;         u32x2 g2[2][4][2];
; #pragma unroll
;         for (int ai = 0; ai < 2; ++ai)
; #pragma unroll
;             for (int m = 0; m < 4; ++m)
; #pragma unroll
;                 for (int bj = 0; bj < 2; ++bj) g2[ai][m][bj] = *(const u32x2*)(zm + (unsigned)(8 + u.pn) * (unsigned)(S * 256) + (r0_ + ai * 128 + m * 16) * 256u + c0_ + bj * 128u);
; #pragma unroll
;         for (int ai = 0; ai < 2; ++ai)
; #pragma unroll
;             for (int m = 0; m < 4; ++m) {
;                 const unsigned row = r0_ + ai * 128 + m * 16;
; #pragma unroll
;                 for (int bj = 0; bj < 2; ++bj) {
;                     float v[8];
; #pragma unroll
;                     for (int e = 0; e < 8; ++e) v[e] = acc[ai][bj][m][e >> 2][e & 3] * (ub(g2[ai][m][bj][e >> 2], e & 3) * (1.f / 255.f));
;                     u32x4 w = {cvtpk(v[0], v[1]), cvtpk(v[2], v[3]), cvtpk(v[4], v[5]), cvtpk(v[6], v[7])};
;                     stg128(mg, row * 4096u + ((unsigned)u.pn * 256u + c0_) * 2u + bj * 256u, w);
;                 }
;             }
;     }
.LBB0_440:
	s_add_i32 s21, s21, 0x2000000
	s_add_u32 s38, s18, s21
	v_lshl_add_u32 v152, s36, 8, v204
	v_mov_b32_e32 v0, v206
	s_addc_u32 s39, s19, 0
	v_mov_b32_e32 v3, v1
	v_lshlrev_b32_e32 v2, 8, v152
	v_lshl_add_u64 v[148:149], s[38:39], 0, v[0:1]
	v_lshl_add_u64 v[150:151], v[148:149], 0, v[2:3]
	global_load_dwordx2 v[164:165], v[150:151], off
	global_load_dwordx2 v[166:167], v[150:151], off offset:128
	v_mov_b32_e32 v151, v1
	v_add_u32_e32 v150, 0x1000, v2
	v_lshl_add_u64 v[150:151], v[148:149], 0, v[150:151]
	global_load_dwordx2 v[168:169], v[150:151], off
	v_mov_b32_e32 v153, v1
	v_mov_b32_e32 v155, v1
	v_mov_b32_e32 v157, v1
	v_lshlrev_b32_e32 v162, 12, v152
	v_add_u32_e32 v152, 0x2000, v2
	v_add_u32_e32 v154, 0x3000, v2
	v_add_u32_e32 v156, 0x8000, v2
	v_add_u32_e32 v158, 0x9000, v2
	v_add_u32_e32 v160, 0xa000, v2
	v_add_u32_e32 v2, 0xb000, v2
	v_mov_b32_e32 v159, v1
	v_mov_b32_e32 v161, v1
	v_lshlrev_b32_e32 v0, 1, v0
	s_lshl_b32 s14, s73, 9
	v_lshl_add_u64 v[152:153], v[148:149], 0, v[152:153]
	v_lshl_add_u64 v[154:155], v[148:149], 0, v[154:155]
	v_lshl_add_u64 v[156:157], v[148:149], 0, v[156:157]
	v_lshl_add_u64 v[2:3], v[148:149], 0, v[2:3]
	v_add3_u32 v0, v162, s14, v0
	v_lshl_add_u64 v[170:171], v[148:149], 0, v[158:159]
	v_lshl_add_u64 v[172:173], v[148:149], 0, v[160:161]
	global_load_dwordx2 v[174:175], v[150:151], off offset:128
	global_load_dwordx2 v[176:177], v[152:153], off
	global_load_dwordx2 v[178:179], v[152:153], off offset:128
	global_load_dwordx2 v[180:181], v[154:155], off
	global_load_dwordx2 v[162:163], v[154:155], off offset:128
	global_load_dwordx2 v[160:161], v[156:157], off
	global_load_dwordx2 v[158:159], v[156:157], off offset:128
	s_nop 0
	global_load_dwordx2 v[156:157], v[170:171], off
	global_load_dwordx2 v[154:155], v[170:171], off offset:128
	global_load_dwordx2 v[152:153], v[172:173], off
	global_load_dwordx2 v[150:151], v[172:173], off offset:128
	global_load_dwordx2 v[148:149], v[2:3], off
	s_nop 0
	global_load_dwordx2 v[2:3], v[2:3], off offset:128
	s_and_b64 vcc, exec, s[4:5]
	s_mov_b32 s73, s20
	s_mov_b32 s36, s22
	s_mov_b64 s[40:41], s[34:35]
	s_mov_b64 s[38:39], s[30:31]
	s_waitcnt vmcnt(0)
	v_lshrrev_b32_e32 v196, 12, v0
	v_bfe_u32 v197, v0, 1, 11
	s_mov_b32 s44, 0x3b808081
	s_movk_i32 s46, 0x800
	v_and_b32_e32 v213, 15, v202
	v_bfe_u32 v214, v202, 2, 4
	v_bfe_u32 v215, v202, 4, 2
	v_and_b32_e32 v216, 3, v202
	v_sub_u32_e32 v217, v214, v213
	v_add_u32_e32 v217, v196, v217
	v_sub_u32_e32 v218, v216, v215
	v_lshl_add_u32 v234, v218, 3, v197
	v_mov_b32_e32 v235, 0
	v_lshl_or_b32 v220, v216, 4, v214
	v_lshlrev_b32_e32 v220, 2, v220
	v_lshl_add_u64 v[236:237], v[234:235], 1, s[8:9]
	v_mov_b32_e32 v239, 0
	v_mul_lo_u32 v238, v217, s46
	v_lshl_add_u64 v[224:225], v[238:239], 1, v[236:237]
	v_cvt_f32_ubyte0_e32 v188, v164
	v_cvt_f32_ubyte1_e32 v189, v164
	v_cvt_f32_ubyte2_e32 v190, v164
	v_cvt_f32_ubyte3_e32 v191, v164
	v_cvt_f32_ubyte0_e32 v192, v165
	v_cvt_f32_ubyte1_e32 v193, v165
	v_cvt_f32_ubyte2_e32 v194, v165
	v_cvt_f32_ubyte3_e32 v195, v165
	v_pk_mul_f32 v[188:189], v[188:189], s[44:45] op_sel_hi:[1,0]
	v_pk_mul_f32 v[190:191], v[190:191], s[44:45] op_sel_hi:[1,0]
	v_pk_mul_f32 v[192:193], v[192:193], s[44:45] op_sel_hi:[1,0]
	v_pk_mul_f32 v[194:195], v[194:195], s[44:45] op_sel_hi:[1,0]
	v_pk_mul_f32 v[128:129], v[128:129], v[188:189]
	v_pk_mul_f32 v[130:131], v[130:131], v[190:191]
	v_pk_mul_f32 v[124:125], v[124:125], v[192:193]
	v_pk_mul_f32 v[126:127], v[126:127], v[194:195]
	v_cvt_pk_bf16_f32 v240, v128, v129
	v_cvt_pk_bf16_f32 v241, v130, v131
	v_cvt_pk_bf16_f32 v242, v124, v125
	v_cvt_pk_bf16_f32 v243, v126, v127
	ds_bpermute_b32 v128, v220, v240
	ds_bpermute_b32 v129, v220, v241
	ds_bpermute_b32 v130, v220, v242
	ds_bpermute_b32 v131, v220, v243
	v_cvt_f32_ubyte0_e32 v188, v166
	v_cvt_f32_ubyte1_e32 v189, v166
	v_cvt_f32_ubyte2_e32 v190, v166
	v_cvt_f32_ubyte3_e32 v191, v166
	v_cvt_f32_ubyte0_e32 v192, v167
	v_cvt_f32_ubyte1_e32 v193, v167
	v_cvt_f32_ubyte2_e32 v194, v167
	v_cvt_f32_ubyte3_e32 v195, v167
	v_pk_mul_f32 v[188:189], v[188:189], s[44:45] op_sel_hi:[1,0]
	v_pk_mul_f32 v[190:191], v[190:191], s[44:45] op_sel_hi:[1,0]
	v_pk_mul_f32 v[192:193], v[192:193], s[44:45] op_sel_hi:[1,0]
	v_pk_mul_f32 v[194:195], v[194:195], s[44:45] op_sel_hi:[1,0]
	v_pk_mul_f32 v[120:121], v[120:121], v[188:189]
	v_pk_mul_f32 v[122:123], v[122:123], v[190:191]
	v_pk_mul_f32 v[116:117], v[116:117], v[192:193]
	v_pk_mul_f32 v[118:119], v[118:119], v[194:195]
	v_cvt_pk_bf16_f32 v244, v120, v121
	v_cvt_pk_bf16_f32 v245, v122, v123
	v_cvt_pk_bf16_f32 v246, v116, v117
	v_cvt_pk_bf16_f32 v247, v118, v119
	ds_bpermute_b32 v120, v220, v244
	ds_bpermute_b32 v121, v220, v245
	ds_bpermute_b32 v122, v220, v246
	ds_bpermute_b32 v123, v220, v247
	s_waitcnt lgkmcnt(4)
	global_store_dwordx4 v[224:225], v[128:131], off
	v_add_u32_e32 v238, 16, v217
	v_mul_lo_u32 v238, v238, s46
	v_lshl_add_u64 v[226:227], v[238:239], 1, v[236:237]
	v_cvt_f32_ubyte0_e32 v188, v168
	v_cvt_f32_ubyte1_e32 v189, v168
	v_cvt_f32_ubyte2_e32 v190, v168
	v_cvt_f32_ubyte3_e32 v191, v168
	v_cvt_f32_ubyte0_e32 v192, v169
	v_cvt_f32_ubyte1_e32 v193, v169
	v_cvt_f32_ubyte2_e32 v194, v169
	v_cvt_f32_ubyte3_e32 v195, v169
	v_pk_mul_f32 v[188:189], v[188:189], s[44:45] op_sel_hi:[1,0]
	v_pk_mul_f32 v[190:191], v[190:191], s[44:45] op_sel_hi:[1,0]
	v_pk_mul_f32 v[192:193], v[192:193], s[44:45] op_sel_hi:[1,0]
	v_pk_mul_f32 v[194:195], v[194:195], s[44:45] op_sel_hi:[1,0]
	v_pk_mul_f32 v[112:113], v[112:113], v[188:189]
	v_pk_mul_f32 v[114:115], v[114:115], v[190:191]
	v_pk_mul_f32 v[108:109], v[108:109], v[192:193]
	v_pk_mul_f32 v[110:111], v[110:111], v[194:195]
	v_cvt_pk_bf16_f32 v248, v112, v113
	v_cvt_pk_bf16_f32 v249, v114, v115
	v_cvt_pk_bf16_f32 v250, v108, v109
	v_cvt_pk_bf16_f32 v251, v110, v111
	ds_bpermute_b32 v112, v220, v248
	ds_bpermute_b32 v113, v220, v249
	ds_bpermute_b32 v114, v220, v250
	ds_bpermute_b32 v115, v220, v251
	s_waitcnt lgkmcnt(4)
; DI unsigned cvtpk(float lo, float hi) { unsigned r; asm volatile("v_cvt_pk_bf16_f32 %0, %1, %2" : "=v"(r) : "v"(lo), "v"(hi)); return r; }
; DI float ub(unsigned w, int i) { return (float)((w >> (8 * i)) & 0xffu); }
;     DI void operator()(const f32x4 (&acc)[2][2][4][2], const pg8::Unit& u, int wr, int wc, int fr, int fq) const {
;     ...
; #pragma unroll
;         for (int ai = 0; ai < 2; ++ai)
; #pragma unroll
;             for (int m = 0; m < 4; ++m) {
;                 const unsigned row = r0_ + ai * 128 + m * 16;
; #pragma unroll
;                 for (int bj = 0; bj < 2; ++bj) {
;                     float v[8];
; #pragma unroll
;                     for (int e = 0; e < 8; ++e) v[e] = acc[ai][bj][m][e >> 2][e & 3] * (ub(g2[ai][m][bj][e >> 2], e & 3) * (1.f / 255.f));
;                     u32x4 w = {cvtpk(v[0], v[1]), cvtpk(v[2], v[3]), cvtpk(v[4], v[5]), cvtpk(v[6], v[7])};
;                     stg128(mg, row * 4096u + ((unsigned)u.pn * 256u + c0_) * 2u + bj * 256u, w);
;                 }
;             }
	global_store_dwordx4 v[224:225], v[120:123], off offset:256
	v_cvt_f32_ubyte0_e32 v188, v174
	v_cvt_f32_ubyte1_e32 v189, v174
	v_cvt_f32_ubyte2_e32 v190, v174
	v_cvt_f32_ubyte3_e32 v191, v174
	v_cvt_f32_ubyte0_e32 v192, v175
	v_cvt_f32_ubyte1_e32 v193, v175
	v_cvt_f32_ubyte2_e32 v194, v175
	v_cvt_f32_ubyte3_e32 v195, v175
	v_pk_mul_f32 v[188:189], v[188:189], s[44:45] op_sel_hi:[1,0]
	v_pk_mul_f32 v[190:191], v[190:191], s[44:45] op_sel_hi:[1,0]
	v_pk_mul_f32 v[192:193], v[192:193], s[44:45] op_sel_hi:[1,0]
	v_pk_mul_f32 v[194:195], v[194:195], s[44:45] op_sel_hi:[1,0]
	v_pk_mul_f32 v[104:105], v[104:105], v[188:189]
	v_pk_mul_f32 v[106:107], v[106:107], v[190:191]
	v_pk_mul_f32 v[100:101], v[100:101], v[192:193]
	v_pk_mul_f32 v[102:103], v[102:103], v[194:195]
	v_cvt_pk_bf16_f32 v252, v104, v105
	v_cvt_pk_bf16_f32 v253, v106, v107
	v_cvt_pk_bf16_f32 v254, v100, v101
	v_cvt_pk_bf16_f32 v255, v102, v103
	ds_bpermute_b32 v104, v220, v252
	ds_bpermute_b32 v105, v220, v253
	ds_bpermute_b32 v106, v220, v254
	ds_bpermute_b32 v107, v220, v255
	s_waitcnt lgkmcnt(4)
	global_store_dwordx4 v[226:227], v[112:115], off
	v_add_u32_e32 v238, 32, v217
	v_mul_lo_u32 v238, v238, s46
	v_lshl_add_u64 v[228:229], v[238:239], 1, v[236:237]
	v_cvt_f32_ubyte0_e32 v188, v176
	v_cvt_f32_ubyte1_e32 v189, v176
	v_cvt_f32_ubyte2_e32 v190, v176
	v_cvt_f32_ubyte3_e32 v191, v176
	v_cvt_f32_ubyte0_e32 v192, v177
	v_cvt_f32_ubyte1_e32 v193, v177
	v_cvt_f32_ubyte2_e32 v194, v177
	v_cvt_f32_ubyte3_e32 v195, v177
	v_pk_mul_f32 v[188:189], v[188:189], s[44:45] op_sel_hi:[1,0]
	v_pk_mul_f32 v[190:191], v[190:191], s[44:45] op_sel_hi:[1,0]
	v_pk_mul_f32 v[192:193], v[192:193], s[44:45] op_sel_hi:[1,0]
	v_pk_mul_f32 v[194:195], v[194:195], s[44:45] op_sel_hi:[1,0]
	v_pk_mul_f32 v[96:97], v[96:97], v[188:189]
	v_pk_mul_f32 v[98:99], v[98:99], v[190:191]
	v_pk_mul_f32 v[92:93], v[92:93], v[192:193]
	v_pk_mul_f32 v[94:95], v[94:95], v[194:195]
	v_cvt_pk_bf16_f32 v240, v96, v97
	v_cvt_pk_bf16_f32 v241, v98, v99
	v_cvt_pk_bf16_f32 v242, v92, v93
	v_cvt_pk_bf16_f32 v243, v94, v95
	ds_bpermute_b32 v96, v220, v240
	ds_bpermute_b32 v97, v220, v241
	ds_bpermute_b32 v98, v220, v242
	ds_bpermute_b32 v99, v220, v243
	s_waitcnt lgkmcnt(4)
	global_store_dwordx4 v[226:227], v[104:107], off offset:256
	v_cvt_f32_ubyte0_e32 v188, v178
	v_cvt_f32_ubyte1_e32 v189, v178
	v_cvt_f32_ubyte2_e32 v190, v178
	v_cvt_f32_ubyte3_e32 v191, v178
	v_cvt_f32_ubyte0_e32 v192, v179
	v_cvt_f32_ubyte1_e32 v193, v179
	v_cvt_f32_ubyte2_e32 v194, v179
	v_cvt_f32_ubyte3_e32 v195, v179
	v_pk_mul_f32 v[188:189], v[188:189], s[44:45] op_sel_hi:[1,0]
	v_pk_mul_f32 v[190:191], v[190:191], s[44:45] op_sel_hi:[1,0]
	v_pk_mul_f32 v[192:193], v[192:193], s[44:45] op_sel_hi:[1,0]
	v_pk_mul_f32 v[194:195], v[194:195], s[44:45] op_sel_hi:[1,0]
	v_pk_mul_f32 v[88:89], v[88:89], v[188:189]
	v_pk_mul_f32 v[90:91], v[90:91], v[190:191]
	v_pk_mul_f32 v[84:85], v[84:85], v[192:193]
	v_pk_mul_f32 v[86:87], v[86:87], v[194:195]
	v_cvt_pk_bf16_f32 v244, v88, v89
	v_cvt_pk_bf16_f32 v245, v90, v91
	v_cvt_pk_bf16_f32 v246, v84, v85
	v_cvt_pk_bf16_f32 v247, v86, v87
	ds_bpermute_b32 v88, v220, v244
	ds_bpermute_b32 v89, v220, v245
	ds_bpermute_b32 v90, v220, v246
	ds_bpermute_b32 v91, v220, v247
	s_waitcnt lgkmcnt(4)
	global_store_dwordx4 v[228:229], v[96:99], off
	v_add_u32_e32 v238, 48, v217
	v_mul_lo_u32 v238, v238, s46
	v_lshl_add_u64 v[230:231], v[238:239], 1, v[236:237]
	v_cvt_f32_ubyte0_e32 v188, v180
	v_cvt_f32_ubyte1_e32 v189, v180
	v_cvt_f32_ubyte2_e32 v190, v180
	v_cvt_f32_ubyte3_e32 v191, v180
	v_cvt_f32_ubyte0_e32 v192, v181
	v_cvt_f32_ubyte1_e32 v193, v181
	v_cvt_f32_ubyte2_e32 v194, v181
	v_cvt_f32_ubyte3_e32 v195, v181
	v_pk_mul_f32 v[188:189], v[188:189], s[44:45] op_sel_hi:[1,0]
	v_pk_mul_f32 v[190:191], v[190:191], s[44:45] op_sel_hi:[1,0]
	v_pk_mul_f32 v[192:193], v[192:193], s[44:45] op_sel_hi:[1,0]
	v_pk_mul_f32 v[194:195], v[194:195], s[44:45] op_sel_hi:[1,0]
	v_pk_mul_f32 v[80:81], v[80:81], v[188:189]
	v_pk_mul_f32 v[82:83], v[82:83], v[190:191]
	v_pk_mul_f32 v[76:77], v[76:77], v[192:193]
	v_pk_mul_f32 v[78:79], v[78:79], v[194:195]
	v_cvt_pk_bf16_f32 v248, v80, v81
	v_cvt_pk_bf16_f32 v249, v82, v83
	v_cvt_pk_bf16_f32 v250, v76, v77
	v_cvt_pk_bf16_f32 v251, v78, v79
	ds_bpermute_b32 v80, v220, v248
	ds_bpermute_b32 v81, v220, v249
	ds_bpermute_b32 v82, v220, v250
	ds_bpermute_b32 v83, v220, v251
	s_waitcnt lgkmcnt(4)
	global_store_dwordx4 v[228:229], v[88:91], off offset:256
	v_cvt_f32_ubyte0_e32 v188, v162
	v_cvt_f32_ubyte1_e32 v189, v162
	v_cvt_f32_ubyte2_e32 v190, v162
	v_cvt_f32_ubyte3_e32 v191, v162
	v_cvt_f32_ubyte0_e32 v192, v163
	v_cvt_f32_ubyte1_e32 v193, v163
	v_cvt_f32_ubyte2_e32 v194, v163
	v_cvt_f32_ubyte3_e32 v195, v163
	v_pk_mul_f32 v[188:189], v[188:189], s[44:45] op_sel_hi:[1,0]
	v_pk_mul_f32 v[190:191], v[190:191], s[44:45] op_sel_hi:[1,0]
	v_pk_mul_f32 v[192:193], v[192:193], s[44:45] op_sel_hi:[1,0]
	v_pk_mul_f32 v[194:195], v[194:195], s[44:45] op_sel_hi:[1,0]
	v_pk_mul_f32 v[72:73], v[72:73], v[188:189]
	v_pk_mul_f32 v[74:75], v[74:75], v[190:191]
	v_pk_mul_f32 v[68:69], v[68:69], v[192:193]
	v_pk_mul_f32 v[70:71], v[70:71], v[194:195]
	v_cvt_pk_bf16_f32 v252, v72, v73
	v_cvt_pk_bf16_f32 v253, v74, v75
	v_cvt_pk_bf16_f32 v254, v68, v69
	v_cvt_pk_bf16_f32 v255, v70, v71
	ds_bpermute_b32 v72, v220, v252
	ds_bpermute_b32 v73, v220, v253
	ds_bpermute_b32 v74, v220, v254
	ds_bpermute_b32 v75, v220, v255
	s_waitcnt lgkmcnt(4)
; DI unsigned cvtpk(float lo, float hi) { unsigned r; asm volatile("v_cvt_pk_bf16_f32 %0, %1, %2" : "=v"(r) : "v"(lo), "v"(hi)); return r; }
; DI float ub(unsigned w, int i) { return (float)((w >> (8 * i)) & 0xffu); }
;     DI void operator()(const f32x4 (&acc)[2][2][4][2], const pg8::Unit& u, int wr, int wc, int fr, int fq) const {
;     ...
; #pragma unroll
;         for (int ai = 0; ai < 2; ++ai)
; #pragma unroll
;             for (int m = 0; m < 4; ++m) {
;                 const unsigned row = r0_ + ai * 128 + m * 16;
; #pragma unroll
;                 for (int bj = 0; bj < 2; ++bj) {
;                     float v[8];
; #pragma unroll
;                     for (int e = 0; e < 8; ++e) v[e] = acc[ai][bj][m][e >> 2][e & 3] * (ub(g2[ai][m][bj][e >> 2], e & 3) * (1.f / 255.f));
;                     u32x4 w = {cvtpk(v[0], v[1]), cvtpk(v[2], v[3]), cvtpk(v[4], v[5]), cvtpk(v[6], v[7])};
;                     stg128(mg, row * 4096u + ((unsigned)u.pn * 256u + c0_) * 2u + bj * 256u, w);
;                 }
;             }
	global_store_dwordx4 v[230:231], v[80:83], off
	v_add_u32_e32 v238, 0x80, v217
	v_mul_lo_u32 v238, v238, s46
	v_lshl_add_u64 v[224:225], v[238:239], 1, v[236:237]
	v_cvt_f32_ubyte0_e32 v188, v160
	v_cvt_f32_ubyte1_e32 v189, v160
	v_cvt_f32_ubyte2_e32 v190, v160
	v_cvt_f32_ubyte3_e32 v191, v160
	v_cvt_f32_ubyte0_e32 v192, v161
	v_cvt_f32_ubyte1_e32 v193, v161
	v_cvt_f32_ubyte2_e32 v194, v161
	v_cvt_f32_ubyte3_e32 v195, v161
	v_pk_mul_f32 v[188:189], v[188:189], s[44:45] op_sel_hi:[1,0]
	v_pk_mul_f32 v[190:191], v[190:191], s[44:45] op_sel_hi:[1,0]
	v_pk_mul_f32 v[192:193], v[192:193], s[44:45] op_sel_hi:[1,0]
	v_pk_mul_f32 v[194:195], v[194:195], s[44:45] op_sel_hi:[1,0]
	v_pk_mul_f32 v[64:65], v[64:65], v[188:189]
	v_pk_mul_f32 v[66:67], v[66:67], v[190:191]
	v_pk_mul_f32 v[60:61], v[60:61], v[192:193]
	v_pk_mul_f32 v[62:63], v[62:63], v[194:195]
	v_cvt_pk_bf16_f32 v240, v64, v65
	v_cvt_pk_bf16_f32 v241, v66, v67
	v_cvt_pk_bf16_f32 v242, v60, v61
	v_cvt_pk_bf16_f32 v243, v62, v63
	ds_bpermute_b32 v64, v220, v240
	ds_bpermute_b32 v65, v220, v241
	ds_bpermute_b32 v66, v220, v242
	ds_bpermute_b32 v67, v220, v243
	s_waitcnt lgkmcnt(4)
	global_store_dwordx4 v[230:231], v[72:75], off offset:256
	v_cvt_f32_ubyte0_e32 v188, v158
	v_cvt_f32_ubyte1_e32 v189, v158
	v_cvt_f32_ubyte2_e32 v190, v158
	v_cvt_f32_ubyte3_e32 v191, v158
	v_cvt_f32_ubyte0_e32 v192, v159
	v_cvt_f32_ubyte1_e32 v193, v159
	v_cvt_f32_ubyte2_e32 v194, v159
	v_cvt_f32_ubyte3_e32 v195, v159
	v_pk_mul_f32 v[188:189], v[188:189], s[44:45] op_sel_hi:[1,0]
	v_pk_mul_f32 v[190:191], v[190:191], s[44:45] op_sel_hi:[1,0]
	v_pk_mul_f32 v[192:193], v[192:193], s[44:45] op_sel_hi:[1,0]
	v_pk_mul_f32 v[194:195], v[194:195], s[44:45] op_sel_hi:[1,0]
	v_pk_mul_f32 v[56:57], v[56:57], v[188:189]
	v_pk_mul_f32 v[58:59], v[58:59], v[190:191]
	v_pk_mul_f32 v[52:53], v[52:53], v[192:193]
	v_pk_mul_f32 v[54:55], v[54:55], v[194:195]
	v_cvt_pk_bf16_f32 v244, v56, v57
	v_cvt_pk_bf16_f32 v245, v58, v59
	v_cvt_pk_bf16_f32 v246, v52, v53
	v_cvt_pk_bf16_f32 v247, v54, v55
	ds_bpermute_b32 v56, v220, v244
	ds_bpermute_b32 v57, v220, v245
	ds_bpermute_b32 v58, v220, v246
	ds_bpermute_b32 v59, v220, v247
	s_waitcnt lgkmcnt(4)
	global_store_dwordx4 v[224:225], v[64:67], off
	v_add_u32_e32 v238, 0x90, v217
	v_mul_lo_u32 v238, v238, s46
	v_lshl_add_u64 v[226:227], v[238:239], 1, v[236:237]
	v_cvt_f32_ubyte0_e32 v188, v156
	v_cvt_f32_ubyte1_e32 v189, v156
	v_cvt_f32_ubyte2_e32 v190, v156
	v_cvt_f32_ubyte3_e32 v191, v156
	v_cvt_f32_ubyte0_e32 v192, v157
	v_cvt_f32_ubyte1_e32 v193, v157
	v_cvt_f32_ubyte2_e32 v194, v157
	v_cvt_f32_ubyte3_e32 v195, v157
	v_pk_mul_f32 v[188:189], v[188:189], s[44:45] op_sel_hi:[1,0]
	v_pk_mul_f32 v[190:191], v[190:191], s[44:45] op_sel_hi:[1,0]
	v_pk_mul_f32 v[192:193], v[192:193], s[44:45] op_sel_hi:[1,0]
	v_pk_mul_f32 v[194:195], v[194:195], s[44:45] op_sel_hi:[1,0]
	v_pk_mul_f32 v[48:49], v[48:49], v[188:189]
	v_pk_mul_f32 v[50:51], v[50:51], v[190:191]
	v_pk_mul_f32 v[44:45], v[44:45], v[192:193]
	v_pk_mul_f32 v[46:47], v[46:47], v[194:195]
	v_cvt_pk_bf16_f32 v248, v48, v49
	v_cvt_pk_bf16_f32 v249, v50, v51
	v_cvt_pk_bf16_f32 v250, v44, v45
	v_cvt_pk_bf16_f32 v251, v46, v47
	ds_bpermute_b32 v48, v220, v248
	ds_bpermute_b32 v49, v220, v249
	ds_bpermute_b32 v50, v220, v250
	ds_bpermute_b32 v51, v220, v251
	s_waitcnt lgkmcnt(4)
	global_store_dwordx4 v[224:225], v[56:59], off offset:256
	v_cvt_f32_ubyte0_e32 v188, v154
	v_cvt_f32_ubyte1_e32 v189, v154
	v_cvt_f32_ubyte2_e32 v190, v154
	v_cvt_f32_ubyte3_e32 v191, v154
	v_cvt_f32_ubyte0_e32 v192, v155
	v_cvt_f32_ubyte1_e32 v193, v155
	v_cvt_f32_ubyte2_e32 v194, v155
	v_cvt_f32_ubyte3_e32 v195, v155
	v_pk_mul_f32 v[188:189], v[188:189], s[44:45] op_sel_hi:[1,0]
	v_pk_mul_f32 v[190:191], v[190:191], s[44:45] op_sel_hi:[1,0]
	v_pk_mul_f32 v[192:193], v[192:193], s[44:45] op_sel_hi:[1,0]
	v_pk_mul_f32 v[194:195], v[194:195], s[44:45] op_sel_hi:[1,0]
	v_pk_mul_f32 v[40:41], v[40:41], v[188:189]
	v_pk_mul_f32 v[42:43], v[42:43], v[190:191]
	v_pk_mul_f32 v[36:37], v[36:37], v[192:193]
	v_pk_mul_f32 v[38:39], v[38:39], v[194:195]
	v_cvt_pk_bf16_f32 v252, v40, v41
	v_cvt_pk_bf16_f32 v253, v42, v43
	v_cvt_pk_bf16_f32 v254, v36, v37
	v_cvt_pk_bf16_f32 v255, v38, v39
	ds_bpermute_b32 v40, v220, v252
	ds_bpermute_b32 v41, v220, v253
	ds_bpermute_b32 v42, v220, v254
	ds_bpermute_b32 v43, v220, v255
	s_waitcnt lgkmcnt(4)
; DI unsigned cvtpk(float lo, float hi) { unsigned r; asm volatile("v_cvt_pk_bf16_f32 %0, %1, %2" : "=v"(r) : "v"(lo), "v"(hi)); return r; }
; DI float ub(unsigned w, int i) { return (float)((w >> (8 * i)) & 0xffu); }
;     DI void operator()(const f32x4 (&acc)[2][2][4][2], const pg8::Unit& u, int wr, int wc, int fr, int fq) const {
;     ...
; #pragma unroll
;         for (int ai = 0; ai < 2; ++ai)
; #pragma unroll
;             for (int m = 0; m < 4; ++m) {
;                 const unsigned row = r0_ + ai * 128 + m * 16;
; #pragma unroll
;                 for (int bj = 0; bj < 2; ++bj) {
;                     float v[8];
; #pragma unroll
;                     for (int e = 0; e < 8; ++e) v[e] = acc[ai][bj][m][e >> 2][e & 3] * (ub(g2[ai][m][bj][e >> 2], e & 3) * (1.f / 255.f));
;                     u32x4 w = {cvtpk(v[0], v[1]), cvtpk(v[2], v[3]), cvtpk(v[4], v[5]), cvtpk(v[6], v[7])};
;                     stg128(mg, row * 4096u + ((unsigned)u.pn * 256u + c0_) * 2u + bj * 256u, w);
;                 }
;             }
	global_store_dwordx4 v[226:227], v[48:51], off
	v_add_u32_e32 v238, 0xa0, v217
	v_mul_lo_u32 v238, v238, s46
	v_lshl_add_u64 v[228:229], v[238:239], 1, v[236:237]
	v_cvt_f32_ubyte0_e32 v188, v152
	v_cvt_f32_ubyte1_e32 v189, v152
	v_cvt_f32_ubyte2_e32 v190, v152
	v_cvt_f32_ubyte3_e32 v191, v152
	v_cvt_f32_ubyte0_e32 v192, v153
	v_cvt_f32_ubyte1_e32 v193, v153
	v_cvt_f32_ubyte2_e32 v194, v153
	v_cvt_f32_ubyte3_e32 v195, v153
	v_pk_mul_f32 v[188:189], v[188:189], s[44:45] op_sel_hi:[1,0]
	v_pk_mul_f32 v[190:191], v[190:191], s[44:45] op_sel_hi:[1,0]
	v_pk_mul_f32 v[192:193], v[192:193], s[44:45] op_sel_hi:[1,0]
	v_pk_mul_f32 v[194:195], v[194:195], s[44:45] op_sel_hi:[1,0]
	v_pk_mul_f32 v[32:33], v[32:33], v[188:189]
	v_pk_mul_f32 v[34:35], v[34:35], v[190:191]
	v_pk_mul_f32 v[28:29], v[28:29], v[192:193]
	v_pk_mul_f32 v[30:31], v[30:31], v[194:195]
	v_cvt_pk_bf16_f32 v240, v32, v33
	v_cvt_pk_bf16_f32 v241, v34, v35
	v_cvt_pk_bf16_f32 v242, v28, v29
	v_cvt_pk_bf16_f32 v243, v30, v31
	ds_bpermute_b32 v32, v220, v240
	ds_bpermute_b32 v33, v220, v241
	ds_bpermute_b32 v34, v220, v242
	ds_bpermute_b32 v35, v220, v243
	s_waitcnt lgkmcnt(4)
	global_store_dwordx4 v[226:227], v[40:43], off offset:256
	v_cvt_f32_ubyte0_e32 v188, v150
	v_cvt_f32_ubyte1_e32 v189, v150
	v_cvt_f32_ubyte2_e32 v190, v150
	v_cvt_f32_ubyte3_e32 v191, v150
	v_cvt_f32_ubyte0_e32 v192, v151
	v_cvt_f32_ubyte1_e32 v193, v151
	v_cvt_f32_ubyte2_e32 v194, v151
	v_cvt_f32_ubyte3_e32 v195, v151
	v_pk_mul_f32 v[188:189], v[188:189], s[44:45] op_sel_hi:[1,0]
	v_pk_mul_f32 v[190:191], v[190:191], s[44:45] op_sel_hi:[1,0]
	v_pk_mul_f32 v[192:193], v[192:193], s[44:45] op_sel_hi:[1,0]
	v_pk_mul_f32 v[194:195], v[194:195], s[44:45] op_sel_hi:[1,0]
	v_pk_mul_f32 v[24:25], v[24:25], v[188:189]
	v_pk_mul_f32 v[26:27], v[26:27], v[190:191]
	v_pk_mul_f32 v[20:21], v[20:21], v[192:193]
	v_pk_mul_f32 v[22:23], v[22:23], v[194:195]
	v_cvt_pk_bf16_f32 v244, v24, v25
	v_cvt_pk_bf16_f32 v245, v26, v27
	v_cvt_pk_bf16_f32 v246, v20, v21
	v_cvt_pk_bf16_f32 v247, v22, v23
	ds_bpermute_b32 v24, v220, v244
	ds_bpermute_b32 v25, v220, v245
	ds_bpermute_b32 v26, v220, v246
	ds_bpermute_b32 v27, v220, v247
	s_waitcnt lgkmcnt(4)
	global_store_dwordx4 v[228:229], v[32:35], off
	v_add_u32_e32 v238, 0xb0, v217
	v_mul_lo_u32 v238, v238, s46
	v_lshl_add_u64 v[230:231], v[238:239], 1, v[236:237]
	v_cvt_f32_ubyte0_e32 v188, v148
	v_cvt_f32_ubyte1_e32 v189, v148
	v_cvt_f32_ubyte2_e32 v190, v148
	v_cvt_f32_ubyte3_e32 v191, v148
	v_cvt_f32_ubyte0_e32 v192, v149
	v_cvt_f32_ubyte1_e32 v193, v149
	v_cvt_f32_ubyte2_e32 v194, v149
	v_cvt_f32_ubyte3_e32 v195, v149
	v_pk_mul_f32 v[188:189], v[188:189], s[44:45] op_sel_hi:[1,0]
	v_pk_mul_f32 v[190:191], v[190:191], s[44:45] op_sel_hi:[1,0]
	v_pk_mul_f32 v[192:193], v[192:193], s[44:45] op_sel_hi:[1,0]
	v_pk_mul_f32 v[194:195], v[194:195], s[44:45] op_sel_hi:[1,0]
	v_pk_mul_f32 v[16:17], v[16:17], v[188:189]
	v_pk_mul_f32 v[18:19], v[18:19], v[190:191]
	v_pk_mul_f32 v[12:13], v[12:13], v[192:193]
	v_pk_mul_f32 v[14:15], v[14:15], v[194:195]
	v_cvt_pk_bf16_f32 v248, v16, v17
	v_cvt_pk_bf16_f32 v249, v18, v19
	v_cvt_pk_bf16_f32 v250, v12, v13
	v_cvt_pk_bf16_f32 v251, v14, v15
	ds_bpermute_b32 v16, v220, v248
	ds_bpermute_b32 v17, v220, v249
	ds_bpermute_b32 v18, v220, v250
	ds_bpermute_b32 v19, v220, v251
	s_waitcnt lgkmcnt(4)
	global_store_dwordx4 v[228:229], v[24:27], off offset:256
	v_cvt_f32_ubyte0_e32 v188, v2
	v_cvt_f32_ubyte1_e32 v189, v2
	v_cvt_f32_ubyte2_e32 v190, v2
	v_cvt_f32_ubyte3_e32 v191, v2
	v_cvt_f32_ubyte0_e32 v192, v3
	v_cvt_f32_ubyte1_e32 v193, v3
	v_cvt_f32_ubyte2_e32 v194, v3
	v_cvt_f32_ubyte3_e32 v195, v3
	v_pk_mul_f32 v[188:189], v[188:189], s[44:45] op_sel_hi:[1,0]
	v_pk_mul_f32 v[190:191], v[190:191], s[44:45] op_sel_hi:[1,0]
	v_pk_mul_f32 v[192:193], v[192:193], s[44:45] op_sel_hi:[1,0]
	v_pk_mul_f32 v[194:195], v[194:195], s[44:45] op_sel_hi:[1,0]
	v_pk_mul_f32 v[8:9], v[8:9], v[188:189]
	v_pk_mul_f32 v[10:11], v[10:11], v[190:191]
	v_pk_mul_f32 v[4:5], v[4:5], v[192:193]
	v_pk_mul_f32 v[6:7], v[6:7], v[194:195]
	v_cvt_pk_bf16_f32 v252, v8, v9
	v_cvt_pk_bf16_f32 v253, v10, v11
	v_cvt_pk_bf16_f32 v254, v4, v5
	v_cvt_pk_bf16_f32 v255, v6, v7
	ds_bpermute_b32 v8, v220, v252
	ds_bpermute_b32 v9, v220, v253
	ds_bpermute_b32 v10, v220, v254
	ds_bpermute_b32 v11, v220, v255
	s_waitcnt lgkmcnt(4)
	global_store_dwordx4 v[230:231], v[16:19], off
	s_waitcnt lgkmcnt(0)
	global_store_dwordx4 v[230:231], v[8:11], off offset:256
	s_cbranch_vccnz .LBB0_453
